# ret_kv item: V row loads issued right after the K loads (same row base), counted waits adjusted
# baseline (speedup 1.0000x reference)
.LBB0_256:
	s_waitcnt vmcnt(0)
	v_mul_f32_e32 v0, 0xbfb8aa3b, v62
	v_rndne_f32_e32 v1, v0
	s_mov_b32 s0, 0xbfb8aa3b
	v_sub_f32_e32 v2, v0, v1
	v_fma_f32 v0, v62, s0, -v0
	v_fmac_f32_e32 v0, 0xb2a5705f, v62
	v_add_f32_e32 v0, v2, v0
	v_cvt_i32_f32_e32 v1, v1
	v_exp_f32_e32 v0, v0
	s_mov_b32 s1, 0x42ce8ed0
	v_cmp_nlt_f32_e32 vcc, s1, v62
	s_mov_b32 s6, 0x3f2aaaab
	v_ldexp_f32 v0, v0, v1
	v_cndmask_b32_e32 v0, 0, v0, vcc
	v_cmp_ngt_f32_e32 vcc, s3, v62
	s_mov_b32 s7, 0x3f317218
	s_mov_b32 s8, 0x33800000
	v_cndmask_b32_e32 v2, v238, v0, vcc
	v_add_f32_e32 v3, 1.0, v2
	v_cvt_f64_f32_e32 v[0:1], v3
	v_frexp_exp_i32_f64_e32 v0, v[0:1]
	v_frexp_mant_f32_e32 v1, v3
	v_cmp_gt_f32_e32 vcc, s6, v1
	v_add_f32_e32 v21, -1.0, v3
	v_sub_f32_e32 v29, v2, v21
	v_subbrev_co_u32_e32 v0, vcc, 0, v0, vcc
	v_cvt_f32_i32_e32 v1, v0
	v_sub_u32_e32 v0, 0, v0
	v_ldexp_f32 v6, v3, v0
	v_sub_f32_e32 v3, v21, v3
	v_add_f32_e32 v3, 1.0, v3
	v_add_f32_e32 v21, 1.0, v6
	v_add_f32_e32 v3, v29, v3
	v_add_f32_e32 v29, -1.0, v21
	v_ldexp_f32 v0, v3, v0
	v_sub_f32_e32 v29, v6, v29
	v_add_f32_e32 v29, v0, v29
	v_add_f32_e32 v7, -1.0, v6
	v_add_f32_e32 v44, v21, v29
	v_add_f32_e32 v3, 1.0, v7
	v_rcp_f32_e32 v45, v44
	v_sub_f32_e32 v3, v6, v3
	v_add_f32_e32 v0, v0, v3
	v_add_f32_e32 v3, v7, v0
	v_mul_f32_e32 v6, v3, v45
	v_mul_f32_e32 v46, v44, v6
	v_sub_f32_e32 v21, v21, v44
	v_add_f32_e32 v21, v29, v21
	v_fma_f32 v29, v6, v44, -v46
	v_fmac_f32_e32 v29, v6, v21
	v_add_f32_e32 v47, v46, v29
	v_sub_f32_e32 v48, v3, v47
	v_sub_f32_e32 v7, v7, v3
	v_sub_f32_e32 v3, v3, v48
	v_sub_f32_e32 v46, v47, v46
	v_add_f32_e32 v0, v0, v7
	v_sub_f32_e32 v3, v3, v47
	v_sub_f32_e32 v29, v46, v29
	v_add_f32_e32 v0, v0, v3
	v_add_f32_e32 v0, v29, v0
	v_add_f32_e32 v3, v48, v0
	v_mul_f32_e32 v7, v45, v3
	v_mul_f32_e32 v46, v44, v7
	v_add_f32_e32 v29, v6, v7
	v_fma_f32 v44, v7, v44, -v46
	v_sub_f32_e32 v6, v29, v6
	v_fmac_f32_e32 v44, v7, v21
	v_sub_f32_e32 v6, v7, v6
	v_add_f32_e32 v7, v46, v44
	v_sub_f32_e32 v21, v3, v7
	v_sub_f32_e32 v46, v7, v46
	v_sub_f32_e32 v44, v46, v44
	v_sub_f32_e32 v46, v48, v3
	v_sub_f32_e32 v3, v3, v21
	v_add_f32_e32 v0, v0, v46
	v_sub_f32_e32 v3, v3, v7
	v_add_f32_e32 v0, v0, v3
	v_add_f32_e32 v0, v44, v0
	v_add_f32_e32 v0, v21, v0
	v_mul_f32_e32 v0, v45, v0
	v_add_f32_e32 v0, v6, v0
	v_add_f32_e32 v3, v29, v0
	v_mul_f32_e32 v7, v3, v3
	v_fmamk_f32 v44, v7, 0x3e9b6dac, v222
	v_mul_f32_e32 v21, v3, v7
	v_fmaak_f32 v7, v7, v44, 0x3f2aaada
	v_ldexp_f32 v6, v3, 1
	v_mul_f32_e32 v7, v21, v7
	v_add_f32_e32 v21, v6, v7
	v_sub_f32_e32 v3, v3, v29
	v_mul_f32_e32 v4, 0x3f317218, v1
	v_sub_f32_e32 v0, v0, v3
	v_sub_f32_e32 v3, v21, v6
	v_fma_f32 v5, v1, s7, -v4
	v_ldexp_f32 v0, v0, 1
	v_sub_f32_e32 v3, v7, v3
	v_fmac_f32_e32 v5, 0xb102e308, v1
	v_add_f32_e32 v0, v0, v3
	v_add_f32_e32 v1, v4, v5
	v_add_f32_e32 v3, v21, v0
	v_add_f32_e32 v6, v1, v3
	v_sub_f32_e32 v4, v1, v4
	v_sub_f32_e32 v4, v5, v4
	v_sub_f32_e32 v5, v3, v21
	v_sub_f32_e32 v7, v6, v1
	v_sub_f32_e32 v0, v0, v5
	v_sub_f32_e32 v3, v3, v7
	v_sub_f32_e32 v7, v6, v7
	v_add_f32_e32 v5, v4, v0
	v_sub_f32_e32 v1, v1, v7
	v_add_f32_e32 v1, v3, v1
	v_sub_f32_e32 v7, v5, v4
	v_add_f32_e32 v1, v5, v1
	v_sub_f32_e32 v5, v5, v7
	v_add_f32_e32 v3, v6, v1
	v_sub_f32_e32 v0, v0, v7
	v_sub_f32_e32 v4, v4, v5
	v_mul_f32_e32 v5, 0xbfb8aa3b, v61
	v_add_f32_e32 v0, v0, v4
	v_sub_f32_e32 v4, v3, v6
	v_rndne_f32_e32 v6, v5
	v_sub_f32_e32 v7, v5, v6
	v_fma_f32 v5, v61, s0, -v5
	v_fmac_f32_e32 v5, 0xb2a5705f, v61
	v_add_f32_e32 v5, v7, v5
	v_exp_f32_e32 v5, v5
	v_cvt_i32_f32_e32 v6, v6
	v_sub_f32_e32 v1, v1, v4
	v_add_f32_e32 v0, v0, v1
	v_add_f32_e32 v3, v3, v0
	v_ldexp_f32 v0, v5, v6
	v_cmp_nlt_f32_e64 s[0:1], s1, v61
	v_cmp_lt_f32_e64 vcc, |v2|, s8
	v_and_b32_e32 v56, 48, v58
	v_cndmask_b32_e64 v0, 0, v0, s[0:1]
	v_cmp_ngt_f32_e64 s[0:1], s3, v61
	s_nop 1
	v_cndmask_b32_e64 v4, v238, v0, s[0:1]
	v_add_f32_e32 v5, 1.0, v4
	v_cvt_f64_f32_e32 v[0:1], v5
	v_frexp_exp_i32_f64_e32 v0, v[0:1]
	v_frexp_mant_f32_e32 v1, v5
	v_cmp_gt_f32_e64 s[0:1], s6, v1
	v_add_f32_e32 v44, -1.0, v5
	v_sub_f32_e32 v45, v4, v44
	v_subbrev_co_u32_e64 v0, s[0:1], 0, v0, s[0:1]
	v_cvt_f32_i32_e32 v1, v0
	v_sub_u32_e32 v0, 0, v0
	v_ldexp_f32 v21, v5, v0
	v_sub_f32_e32 v5, v44, v5
	v_add_f32_e32 v5, 1.0, v5
	v_add_f32_e32 v44, 1.0, v21
	v_add_f32_e32 v5, v45, v5
	v_add_f32_e32 v45, -1.0, v44
	v_ldexp_f32 v0, v5, v0
	v_sub_f32_e32 v45, v21, v45
	v_add_f32_e32 v45, v0, v45
	v_add_f32_e32 v29, -1.0, v21
	v_add_f32_e32 v46, v44, v45
	v_add_f32_e32 v5, 1.0, v29
	v_rcp_f32_e32 v47, v46
	v_sub_f32_e32 v5, v21, v5
	v_add_f32_e32 v0, v0, v5
	v_add_f32_e32 v5, v29, v0
	v_mul_f32_e32 v21, v5, v47
	v_mul_f32_e32 v48, v46, v21
	v_sub_f32_e32 v44, v44, v46
	v_add_f32_e32 v44, v45, v44
	v_fma_f32 v45, v21, v46, -v48
	v_fmac_f32_e32 v45, v21, v44
	v_add_f32_e32 v49, v48, v45
	v_sub_f32_e32 v50, v5, v49
	v_sub_f32_e32 v29, v29, v5
	v_sub_f32_e32 v5, v5, v50
	v_sub_f32_e32 v48, v49, v48
	v_add_f32_e32 v0, v0, v29
	v_sub_f32_e32 v5, v5, v49
	v_sub_f32_e32 v45, v48, v45
	v_add_f32_e32 v0, v0, v5
	v_add_f32_e32 v0, v45, v0
	v_add_f32_e32 v5, v50, v0
	v_mul_f32_e32 v29, v47, v5
	v_mul_f32_e32 v48, v46, v29
	v_add_f32_e32 v45, v21, v29
	v_fma_f32 v46, v29, v46, -v48
	v_sub_f32_e32 v21, v45, v21
	v_fmac_f32_e32 v46, v29, v44
	v_sub_f32_e32 v21, v29, v21
	v_add_f32_e32 v29, v48, v46
	v_sub_f32_e32 v44, v5, v29
	v_sub_f32_e32 v48, v29, v48
	v_sub_f32_e32 v46, v48, v46
	v_sub_f32_e32 v48, v50, v5
	v_sub_f32_e32 v5, v5, v44
	v_add_f32_e32 v0, v0, v48
	v_sub_f32_e32 v5, v5, v29
	v_add_f32_e32 v0, v0, v5
	v_add_f32_e32 v0, v46, v0
	v_add_f32_e32 v0, v44, v0
	v_mul_f32_e32 v0, v47, v0
	v_add_f32_e32 v0, v21, v0
	v_add_f32_e32 v5, v45, v0
	v_mul_f32_e32 v29, v5, v5
	v_fmamk_f32 v46, v29, 0x3e9b6dac, v222
	v_mul_f32_e32 v44, v5, v29
	v_fmaak_f32 v29, v29, v46, 0x3f2aaada
	v_ldexp_f32 v21, v5, 1
	v_mul_f32_e32 v29, v44, v29
	v_add_f32_e32 v44, v21, v29
	v_sub_f32_e32 v5, v5, v45
	v_mul_f32_e32 v6, 0x3f317218, v1
	v_sub_f32_e32 v0, v0, v5
	v_sub_f32_e32 v5, v44, v21
	v_fma_f32 v7, v1, s7, -v6
	v_ldexp_f32 v0, v0, 1
	v_sub_f32_e32 v5, v29, v5
	v_fmac_f32_e32 v7, 0xb102e308, v1
	v_add_f32_e32 v0, v0, v5
	v_add_f32_e32 v1, v6, v7
	v_add_f32_e32 v5, v44, v0
	v_add_f32_e32 v21, v1, v5
	v_sub_f32_e32 v6, v1, v6
	v_sub_f32_e32 v6, v7, v6
	v_sub_f32_e32 v7, v5, v44
	v_sub_f32_e32 v29, v21, v1
	v_sub_f32_e32 v0, v0, v7
	v_sub_f32_e32 v5, v5, v29
	v_sub_f32_e32 v29, v21, v29
	v_add_f32_e32 v7, v6, v0
	v_sub_f32_e32 v1, v1, v29
	v_add_f32_e32 v1, v5, v1
	v_sub_f32_e32 v29, v7, v6
	v_add_f32_e32 v1, v7, v1
	v_sub_f32_e32 v7, v7, v29
	v_add_f32_e32 v5, v21, v1
	v_sub_f32_e32 v0, v0, v29
	v_sub_f32_e32 v6, v6, v7
	v_add_f32_e32 v0, v0, v6
	v_sub_f32_e32 v6, v5, v21
	v_sub_f32_e32 v1, v1, v6
	v_add_f32_e32 v0, v0, v1
	v_sub_u32_e32 v1, 0x7f, v59
	v_cvt_f32_i32_e32 v1, v1
	v_cmp_neq_f32_e64 s[0:1], s21, v2
	v_add_f32_e32 v0, v5, v0
	v_cmp_neq_f32_e64 s[36:37], s21, v4
	v_cndmask_b32_e64 v3, v238, v3, s[0:1]
	v_cmp_lt_f32_e64 s[0:1], |v4|, s8
	v_cndmask_b32_e64 v0, v238, v0, s[36:37]
	v_cndmask_b32_e32 v2, v3, v2, vcc
	v_cndmask_b32_e64 v0, v0, v4, s[0:1]
	v_mul_f32_e64 v1, v1, -v0
	v_mul_f32_e32 v0, 0x3fb8aa3b, v1
	s_mov_b32 s0, 0x3fb8aa3b
	v_fma_f32 v4, v1, s0, -v0
	v_rndne_f32_e32 v5, v0
	v_fmac_f32_e32 v4, 0x32a5705f, v1
	v_sub_f32_e32 v0, v0, v5
	v_cvt_f32_i32_e32 v3, v59
	v_add_f32_e32 v0, v0, v4
	v_exp_f32_e32 v4, v0
	v_cvt_i32_f32_e32 v5, v5
	v_mul_f32_e64 v2, v3, -v2
	v_mul_f32_e32 v3, 0x3fb8aa3b, v2
	v_rndne_f32_e32 v6, v3
	v_ldexp_f32 v4, v4, v5
	v_fma_f32 v5, v2, s0, -v3
	v_fmac_f32_e32 v5, 0x32a5705f, v2
	v_sub_f32_e32 v3, v3, v6
	v_add_f32_e32 v3, v3, v5
	v_exp_f32_e32 v3, v3
	v_cvt_i32_f32_e32 v5, v6
	s_mov_b32 s1, 0xc2ce8ed0
	v_cmp_ngt_f32_e32 vcc, s1, v1
	s_mov_b32 s0, 0x42b17218
	v_lshlrev_b32_e32 v6, 1, v59
	v_cndmask_b32_e32 v4, 0, v4, vcc
	v_cmp_nlt_f32_e32 vcc, s0, v1
	v_ldexp_f32 v1, v3, v5
	v_and_b32_e32 v0, 15, v58
	v_cndmask_b32_e32 v21, v238, v4, vcc
	v_cmp_ngt_f32_e32 vcc, s1, v2
	v_mul_u32_u24_e32 v4, 0x1100, v60
	v_lshlrev_b32_e32 v4, 1, v4
	v_cndmask_b32_e32 v1, 0, v1, vcc
	v_cmp_nlt_f32_e32 vcc, s0, v2
	s_movk_i32 s0, 0x1100
	s_nop 0
	v_cndmask_b32_e32 v3, v238, v1, vcc
	v_mul_f32_e32 v1, v21, v42
	v_bfe_u32 v2, v1, 16, 1
	v_add3_u32 v2, v1, v2, s97
	v_mad_u32_u24 v1, v60, s0, v59
	v_lshl_add_u32 v1, v1, 1, s20
	ds_write_b16_d16_hi v1, v2
	v_mul_f32_e32 v2, v3, v42
	v_bfe_u32 v5, v2, 16, 1
	v_add3_u32 v5, v2, v5, s97
	v_add3_u32 v2, s20, v6, v4
	ds_write_b16_d16_hi v2, v5 offset:17408
	v_mul_f32_e32 v5, v21, v43
	v_bfe_u32 v7, v5, 16, 1
	v_add3_u32 v5, v5, v7, s97
	v_add3_u32 v42, s20, v4, v6
	v_mul_f32_e32 v4, v3, v43
	ds_write_b16_d16_hi v42, v5 offset:272
	v_bfe_u32 v5, v4, 16, 1
	v_add3_u32 v4, v4, v5, s97
	ds_write_b16_d16_hi v2, v4 offset:17680
	v_mul_f32_e32 v4, v21, v40
	v_bfe_u32 v5, v4, 16, 1
	v_add3_u32 v4, v4, v5, s97
	ds_write_b16_d16_hi v1, v4 offset:544
	v_mul_f32_e32 v4, v3, v40
	v_bfe_u32 v5, v4, 16, 1
	v_add3_u32 v4, v4, v5, s97
	ds_write_b16_d16_hi v2, v4 offset:17952
	v_mul_f32_e32 v4, v21, v41
	v_bfe_u32 v5, v4, 16, 1
	v_add3_u32 v4, v4, v5, s97
	ds_write_b16_d16_hi v42, v4 offset:816
	v_mul_f32_e32 v4, v3, v41
	v_bfe_u32 v5, v4, 16, 1
	v_add3_u32 v4, v4, v5, s97
	ds_write_b16_d16_hi v2, v4 offset:18224
	v_mul_f32_e32 v4, v21, v38
	v_bfe_u32 v5, v4, 16, 1
	v_add3_u32 v4, v4, v5, s97
	ds_write_b16_d16_hi v1, v4 offset:1088
	v_mul_f32_e32 v4, v3, v38
	v_bfe_u32 v5, v4, 16, 1
	v_add3_u32 v4, v4, v5, s97
	ds_write_b16_d16_hi v2, v4 offset:18496
	v_mul_f32_e32 v4, v21, v39
	v_bfe_u32 v5, v4, 16, 1
	v_add3_u32 v4, v4, v5, s97
	ds_write_b16_d16_hi v42, v4 offset:1360
	v_mul_f32_e32 v4, v3, v39
	v_bfe_u32 v5, v4, 16, 1
	v_add3_u32 v4, v4, v5, s97
	ds_write_b16_d16_hi v2, v4 offset:18768
	v_mul_f32_e32 v4, v21, v36
	v_bfe_u32 v5, v4, 16, 1
	v_add3_u32 v4, v4, v5, s97
	ds_write_b16_d16_hi v1, v4 offset:1632
	v_mul_f32_e32 v4, v3, v36
	v_bfe_u32 v5, v4, 16, 1
	v_add3_u32 v4, v4, v5, s97
	ds_write_b16_d16_hi v2, v4 offset:19040
	v_mul_f32_e32 v4, v21, v37
	v_bfe_u32 v5, v4, 16, 1
	v_add3_u32 v4, v4, v5, s97
	ds_write_b16_d16_hi v42, v4 offset:1904
	v_mul_f32_e32 v4, v3, v37
	v_bfe_u32 v5, v4, 16, 1
	v_add3_u32 v4, v4, v5, s97
	ds_write_b16_d16_hi v2, v4 offset:19312
	v_mul_f32_e32 v4, v21, v34
	v_bfe_u32 v5, v4, 16, 1
	v_add3_u32 v4, v4, v5, s97
	ds_write_b16_d16_hi v1, v4 offset:2176
	v_mul_f32_e32 v4, v3, v34
	v_bfe_u32 v5, v4, 16, 1
	v_add3_u32 v4, v4, v5, s97
	ds_write_b16_d16_hi v2, v4 offset:19584
	v_mul_f32_e32 v4, v21, v35
	v_bfe_u32 v5, v4, 16, 1
	v_add3_u32 v4, v4, v5, s97
	ds_write_b16_d16_hi v42, v4 offset:2448
	v_mul_f32_e32 v4, v3, v35
	v_bfe_u32 v5, v4, 16, 1
	v_add3_u32 v4, v4, v5, s97
	ds_write_b16_d16_hi v2, v4 offset:19856
	v_mul_f32_e32 v4, v21, v32
	v_bfe_u32 v5, v4, 16, 1
	v_add3_u32 v4, v4, v5, s97
	ds_write_b16_d16_hi v1, v4 offset:2720
	v_mul_f32_e32 v4, v3, v32
	v_bfe_u32 v5, v4, 16, 1
	v_add3_u32 v4, v4, v5, s97
	ds_write_b16_d16_hi v2, v4 offset:20128
	v_mul_f32_e32 v4, v21, v33
	v_bfe_u32 v5, v4, 16, 1
	v_add3_u32 v4, v4, v5, s97
	ds_write_b16_d16_hi v42, v4 offset:2992
	v_mul_f32_e32 v4, v3, v33
	v_bfe_u32 v5, v4, 16, 1
	v_add3_u32 v4, v4, v5, s97
	ds_write_b16_d16_hi v2, v4 offset:20400
	v_mul_f32_e32 v4, v21, v30
	v_bfe_u32 v5, v4, 16, 1
	v_add3_u32 v4, v4, v5, s97
	ds_write_b16_d16_hi v1, v4 offset:3264
	v_mul_f32_e32 v4, v3, v30
	v_bfe_u32 v5, v4, 16, 1
	v_add3_u32 v4, v4, v5, s97
	ds_write_b16_d16_hi v2, v4 offset:20672
	v_mul_f32_e32 v4, v21, v31
	v_bfe_u32 v5, v4, 16, 1
	v_add3_u32 v4, v4, v5, s97
	ds_write_b16_d16_hi v42, v4 offset:3536
	v_mul_f32_e32 v4, v3, v31
	v_bfe_u32 v5, v4, 16, 1
	v_add3_u32 v4, v4, v5, s97
	ds_write_b16_d16_hi v2, v4 offset:20944
	v_mul_f32_e32 v4, v21, v28
	v_bfe_u32 v5, v4, 16, 1
	v_add3_u32 v4, v4, v5, s97
	ds_write_b16_d16_hi v1, v4 offset:3808
	v_mul_f32_e32 v4, v3, v28
	v_bfe_u32 v5, v4, 16, 1
	v_add3_u32 v4, v4, v5, s97
	ds_write_b16_d16_hi v2, v4 offset:21216
	v_mul_f32_e32 v4, v21, v19
	v_bfe_u32 v5, v4, 16, 1
	v_add3_u32 v4, v4, v5, s97
	ds_write_b16_d16_hi v42, v4 offset:4080
	v_mul_f32_e32 v4, v3, v19
	v_bfe_u32 v5, v4, 16, 1
	v_add3_u32 v4, v4, v5, s97
	ds_write_b16_d16_hi v2, v4 offset:21488
	v_mul_f32_e32 v4, v21, v26
	v_bfe_u32 v5, v4, 16, 1
	v_add3_u32 v4, v4, v5, s97
	ds_write_b16_d16_hi v1, v4 offset:4352
	v_mul_f32_e32 v4, v3, v26
	v_bfe_u32 v5, v4, 16, 1
	v_add3_u32 v4, v4, v5, s97
	ds_write_b16_d16_hi v2, v4 offset:21760
	v_mul_f32_e32 v4, v21, v27
	v_bfe_u32 v5, v4, 16, 1
	v_add3_u32 v4, v4, v5, s97
	ds_write_b16_d16_hi v42, v4 offset:4624
	v_mul_f32_e32 v4, v3, v27
	v_bfe_u32 v5, v4, 16, 1
	v_add3_u32 v4, v4, v5, s97
	ds_write_b16_d16_hi v2, v4 offset:22032
	v_mul_f32_e32 v4, v21, v24
	v_bfe_u32 v5, v4, 16, 1
	v_add3_u32 v4, v4, v5, s97
	ds_write_b16_d16_hi v1, v4 offset:4896
	v_mul_f32_e32 v4, v3, v24
	v_bfe_u32 v5, v4, 16, 1
	v_add3_u32 v4, v4, v5, s97
	ds_write_b16_d16_hi v2, v4 offset:22304
	v_mul_f32_e32 v4, v21, v25
	v_bfe_u32 v5, v4, 16, 1
	v_add3_u32 v4, v4, v5, s97
	ds_write_b16_d16_hi v42, v4 offset:5168
	v_mul_f32_e32 v4, v3, v25
	v_bfe_u32 v5, v4, 16, 1
	v_add3_u32 v4, v4, v5, s97
	ds_write_b16_d16_hi v2, v4 offset:22576
	v_mul_f32_e32 v4, v21, v22
	v_bfe_u32 v5, v4, 16, 1
	v_add3_u32 v4, v4, v5, s97
	ds_write_b16_d16_hi v1, v4 offset:5440
	v_mul_f32_e32 v4, v3, v22
	v_bfe_u32 v5, v4, 16, 1
	v_add3_u32 v4, v4, v5, s97
	ds_write_b16_d16_hi v2, v4 offset:22848
	v_mul_f32_e32 v4, v21, v23
	v_bfe_u32 v5, v4, 16, 1
	v_add3_u32 v4, v4, v5, s97
	ds_write_b16_d16_hi v42, v4 offset:5712
	v_mul_f32_e32 v4, v3, v23
	v_bfe_u32 v5, v4, 16, 1
	v_add3_u32 v4, v4, v5, s97
	ds_write_b16_d16_hi v2, v4 offset:23120
	v_mul_f32_e32 v4, v21, v16
	v_bfe_u32 v5, v4, 16, 1
	v_add3_u32 v4, v4, v5, s97
	ds_write_b16_d16_hi v1, v4 offset:5984
	v_mul_f32_e32 v16, v3, v16
	v_bfe_u32 v19, v16, 16, 1
	v_add3_u32 v16, v16, v19, s97
	ds_write_b16_d16_hi v2, v16 offset:23392
	v_mul_f32_e32 v16, v21, v17
	v_bfe_u32 v19, v16, 16, 1
	v_add3_u32 v16, v16, v19, s97
	ds_write_b16_d16_hi v42, v16 offset:6256
	v_mul_f32_e32 v16, v3, v17
	v_bfe_u32 v17, v16, 16, 1
	v_add3_u32 v16, v16, v17, s97
	ds_write_b16_d16_hi v2, v16 offset:23664
	v_mul_f32_e32 v16, v21, v14
	v_bfe_u32 v17, v16, 16, 1
	v_add3_u32 v16, v16, v17, s97
	v_mul_f32_e32 v14, v3, v14
	ds_write_b16_d16_hi v1, v16 offset:6528
	v_bfe_u32 v16, v14, 16, 1
	v_add3_u32 v14, v14, v16, s97
	ds_write_b16_d16_hi v2, v14 offset:23936
	v_mul_f32_e32 v14, v21, v15
	v_bfe_u32 v8, v14, 16, 1
	v_add3_u32 v8, v14, v8, s97
	ds_write_b16_d16_hi v42, v8 offset:6800
	v_mul_f32_e32 v8, v3, v15
	v_bfe_u32 v9, v8, 16, 1
	v_add3_u32 v8, v8, v9, s97
	ds_write_b16_d16_hi v2, v8 offset:24208
	v_mul_f32_e32 v8, v21, v12
	v_bfe_u32 v9, v8, 16, 1
	v_add3_u32 v8, v8, v9, s97
	ds_write_b16_d16_hi v1, v8 offset:7072
	v_mul_f32_e32 v8, v3, v12
	v_bfe_u32 v9, v8, 16, 1
	v_add3_u32 v8, v8, v9, s97
	ds_write_b16_d16_hi v2, v8 offset:24480
	v_mul_f32_e32 v8, v21, v13
	v_bfe_u32 v9, v8, 16, 1
	v_add3_u32 v8, v8, v9, s97
	ds_write_b16_d16_hi v42, v8 offset:7344
	v_mul_f32_e32 v8, v3, v13
	v_bfe_u32 v9, v8, 16, 1
	v_add3_u32 v8, v8, v9, s97
	ds_write_b16_d16_hi v2, v8 offset:24752
	v_mul_f32_e32 v8, v21, v10
	v_bfe_u32 v9, v8, 16, 1
	v_add3_u32 v8, v8, v9, s97
	ds_write_b16_d16_hi v1, v8 offset:7616
	v_mul_f32_e32 v8, v3, v10
	v_bfe_u32 v9, v8, 16, 1
	v_add3_u32 v8, v8, v9, s97
	ds_write_b16_d16_hi v2, v8 offset:25024
	v_mul_f32_e32 v8, v21, v11
	v_bfe_u32 v9, v8, 16, 1
	v_add3_u32 v8, v8, v9, s97
	ds_write_b16_d16_hi v42, v8 offset:7888
	v_mul_f32_e32 v8, v3, v11
	v_bfe_u32 v9, v8, 16, 1
	v_add3_u32 v8, v8, v9, s97
	ds_write_b16_d16_hi v2, v8 offset:25296
	v_mul_f32_e32 v8, v21, v20
	v_bfe_u32 v9, v8, 16, 1
	v_add3_u32 v8, v8, v9, s97
	ds_write_b16_d16_hi v1, v8 offset:8160
	v_mul_f32_e32 v8, v3, v20
	v_bfe_u32 v9, v8, 16, 1
	v_add3_u32 v8, v8, v9, s97
	ds_write_b16_d16_hi v2, v8 offset:25568
	v_mul_f32_e32 v8, v21, v18
	v_bfe_u32 v9, v8, 16, 1
	v_add3_u32 v8, v8, v9, s97
	v_mul_f32_e32 v3, v3, v18
	ds_write_b16_d16_hi v42, v8 offset:8432
	v_bfe_u32 v8, v3, 16, 1
	v_add3_u32 v3, v3, v8, s97
	s_mov_b32 s0, 0xfffffe0
	ds_write_b16_d16_hi v2, v3 offset:25840
	s_waitcnt vmcnt(3)
	ds_write_b16 v1, v156 offset:34816
	ds_write_b16_d16_hi v2, v156 offset:35088
	ds_write_b16 v1, v157 offset:35360
	ds_write_b16_d16_hi v2, v157 offset:35632
	ds_write_b16 v1, v158 offset:35904
	ds_write_b16_d16_hi v2, v158 offset:36176
	ds_write_b16 v1, v159 offset:36448
	ds_write_b16_d16_hi v2, v159 offset:36720
	s_waitcnt vmcnt(2)
	ds_write_b16 v1, v160 offset:36992
	ds_write_b16_d16_hi v2, v160 offset:37264
	ds_write_b16 v1, v161 offset:37536
	ds_write_b16_d16_hi v2, v161 offset:37808
	ds_write_b16 v1, v162 offset:38080
	ds_write_b16_d16_hi v2, v162 offset:38352
	ds_write_b16 v1, v163 offset:38624
	ds_write_b16_d16_hi v2, v163 offset:38896
	s_waitcnt vmcnt(1)
	ds_write_b16 v1, v164 offset:39168
	ds_write_b16_d16_hi v2, v164 offset:39440
	ds_write_b16 v1, v165 offset:39712
	ds_write_b16_d16_hi v2, v165 offset:39984
	ds_write_b16 v1, v166 offset:40256
	ds_write_b16_d16_hi v2, v166 offset:40528
	ds_write_b16 v1, v167 offset:40800
	ds_write_b16_d16_hi v2, v167 offset:41072
	s_waitcnt vmcnt(0)
	ds_write_b16 v1, v168 offset:41344
	ds_write_b16_d16_hi v2, v168 offset:41616
	ds_write_b16 v1, v169 offset:41888
	ds_write_b16_d16_hi v2, v169 offset:42160
	ds_write_b16 v1, v170 offset:42432
	ds_write_b16_d16_hi v2, v170 offset:42704
	ds_write_b16 v1, v171 offset:42976
	ds_write_b16_d16_hi v2, v171 offset:43248
	v_and_or_b32 v1, v59, s0, v0
	v_add_u32_e32 v6, s20, v56
	s_movk_i32 s0, 0x110
	v_mad_u64_u32 v[54:55], s[0:1], v1, s0, v[6:7]
	s_waitcnt lgkmcnt(0)
	s_barrier
	ds_read_b128 v[2:5], v54
	ds_read_b128 v[38:41], v54 offset:64
	ds_read_b128 v[34:37], v54 offset:4352
	v_mul_u32_u24_e32 v1, 0x88, v0
	v_lshl_add_u32 v1, v1, 1, v6
	ds_read_b128 v[6:9], v1 offset:34816
	ds_read_b128 v[14:17], v1 offset:39168
	ds_read_b128 v[22:25], v1 offset:43520
	ds_read_b128 v[46:49], v1 offset:43584
	ds_read_b128 v[30:33], v1 offset:47872
	ds_read_b128 v[50:53], v1 offset:47936
	s_waitcnt lgkmcnt(5)
	v_mfma_f32_16x16x32_bf16 v[10:13], v[2:5], v[6:9], 0
	ds_read_b128 v[42:45], v1 offset:39232
	v_lshlrev_b32_e32 v0, 8, v0
	s_waitcnt lgkmcnt(5)
	v_mfma_f32_16x16x32_bf16 v[18:21], v[2:5], v[14:17], 0
	s_waitcnt lgkmcnt(4)
	v_mfma_f32_16x16x32_bf16 v[26:29], v[2:5], v[22:25], 0
	s_waitcnt lgkmcnt(2)
	v_mfma_f32_16x16x32_bf16 v[2:5], v[2:5], v[30:33], 0
	v_mfma_f32_16x16x32_bf16 v[6:9], v[34:37], v[6:9], 0
	v_mfma_f32_16x16x32_bf16 v[14:17], v[34:37], v[14:17], 0
	v_mfma_f32_16x16x32_bf16 v[22:25], v[34:37], v[22:25], 0
	v_mfma_f32_16x16x32_bf16 v[30:33], v[34:37], v[30:33], 0
	ds_read_b128 v[34:37], v1 offset:34880
	s_waitcnt lgkmcnt(0)
	v_mfma_f32_16x16x32_bf16 v[10:13], v[38:41], v[34:37], v[10:13]
	v_mfma_f32_16x16x32_bf16 v[18:21], v[38:41], v[42:45], v[18:21]
	v_mfma_f32_16x16x32_bf16 v[26:29], v[38:41], v[46:49], v[26:29]
	v_mfma_f32_16x16x32_bf16 v[2:5], v[38:41], v[50:53], v[2:5]
	ds_read_b128 v[38:41], v54 offset:4416
	s_waitcnt lgkmcnt(0)
	v_mfma_f32_16x16x32_bf16 v[6:9], v[38:41], v[34:37], v[6:9]
	ds_read_b128 v[34:37], v54 offset:128
	v_mfma_f32_16x16x32_bf16 v[14:17], v[38:41], v[42:45], v[14:17]
	ds_read_b128 v[42:45], v1 offset:39296
	v_mfma_f32_16x16x32_bf16 v[22:25], v[38:41], v[46:49], v[22:25]
	ds_read_b128 v[46:49], v1 offset:43648
	v_mfma_f32_16x16x32_bf16 v[30:33], v[38:41], v[50:53], v[30:33]
	ds_read_b128 v[38:41], v1 offset:34944
	ds_read_b128 v[50:53], v1 offset:48000
	s_waitcnt lgkmcnt(1)
	v_mfma_f32_16x16x32_bf16 v[10:13], v[34:37], v[38:41], v[10:13]
	v_mfma_f32_16x16x32_bf16 v[18:21], v[34:37], v[42:45], v[18:21]
	v_mfma_f32_16x16x32_bf16 v[26:29], v[34:37], v[46:49], v[26:29]
	s_waitcnt lgkmcnt(0)
	v_mfma_f32_16x16x32_bf16 v[2:5], v[34:37], v[50:53], v[2:5]
	ds_read_b128 v[34:37], v54 offset:4480
	s_waitcnt lgkmcnt(0)
	v_mfma_f32_16x16x32_bf16 v[6:9], v[34:37], v[38:41], v[6:9]
	ds_read_b128 v[38:41], v54 offset:192
	v_mfma_f32_16x16x32_bf16 v[14:17], v[34:37], v[42:45], v[14:17]
	ds_read_b128 v[42:45], v1 offset:39360
	v_mfma_f32_16x16x32_bf16 v[22:25], v[34:37], v[46:49], v[22:25]
	ds_read_b128 v[46:49], v1 offset:43712
	v_mfma_f32_16x16x32_bf16 v[30:33], v[34:37], v[50:53], v[30:33]
	ds_read_b128 v[34:37], v1 offset:35008
	ds_read_b128 v[50:53], v1 offset:48064
	v_and_b32_e32 v1, 32, v59
	s_waitcnt lgkmcnt(1)
	v_mfma_f32_16x16x32_bf16 v[10:13], v[38:41], v[34:37], v[10:13]
	v_lshl_or_b32 v1, v1, 2, v56
	v_mfma_f32_16x16x32_bf16 v[18:21], v[38:41], v[42:45], v[18:21]
	v_mfma_f32_16x16x32_bf16 v[26:29], v[38:41], v[46:49], v[26:29]
	s_waitcnt lgkmcnt(0)
	v_mfma_f32_16x16x32_bf16 v[2:5], v[38:41], v[50:53], v[2:5]
	ds_read_b128 v[38:41], v54 offset:4544
	s_waitcnt lgkmcnt(0)
	v_mfma_f32_16x16x32_bf16 v[6:9], v[38:41], v[34:37], v[6:9]
	v_ashrrev_i32_e32 v34, 7, v58
	v_ashrrev_i32_e32 v35, 31, v34
	v_lshlrev_b64 v[34:35], 14, v[34:35]
	v_or3_b32 v34, v34, v0, v1
	v_lshl_add_u64 v[0:1], s[30:31], 0, v[34:35]
	global_store_dwordx4 v[0:1], v[10:13], off
	v_mfma_f32_16x16x32_bf16 v[14:17], v[38:41], v[42:45], v[14:17]
	s_nop 0
	v_add_co_u32_e32 v10, vcc, 0x1000, v0
	v_mfma_f32_16x16x32_bf16 v[22:25], v[38:41], v[46:49], v[22:25]
	s_nop 0
	v_addc_co_u32_e32 v11, vcc, 0, v1, vcc
	v_add_co_u32_e32 v12, vcc, 0x2000, v0
	global_store_dwordx4 v[10:11], v[18:21], off
	s_nop 0
	v_addc_co_u32_e32 v13, vcc, 0, v1, vcc
	v_add_co_u32_e32 v18, vcc, 0x3000, v0
	v_mfma_f32_16x16x32_bf16 v[30:33], v[38:41], v[50:53], v[30:33]
	s_nop 0
	v_addc_co_u32_e32 v19, vcc, 0, v1, vcc
	global_store_dwordx4 v[12:13], v[26:29], off
	global_store_dwordx4 v[18:19], v[2:5], off
	global_store_dwordx4 v[0:1], v[6:9], off offset:64
	global_store_dwordx4 v[10:11], v[14:17], off offset:64
	global_store_dwordx4 v[12:13], v[22:25], off offset:64
	s_nop 0
	global_store_dwordx4 v[18:19], v[30:33], off offset:64
	s_barrier

.LBB0_269:
	s_and_b32 s27, s27, 3
	s_or_b32 s36, s27, s57
	v_ashrrev_i32_e32 v59, 1, v58
	s_ashr_i32 s37, s36, 31
	v_add_u32_e32 v0, s26, v59
	s_lshl_b64 s[36:37], s[36:37], 2
	v_readlane_b32 s40, v253, 48
	v_ashrrev_i32_e32 v1, 31, v0
	v_readlane_b32 s4, v253, 16
	v_readlane_b32 s41, v253, 49
	s_add_u32 s36, s40, s36
	v_lshlrev_b64 v[0:1], 12, v[0:1]
	v_readlane_b32 s5, v253, 17
	s_addc_u32 s37, s41, s37
	v_and_b32_e32 v60, 1, v58
	v_lshl_add_u64 v[0:1], s[4:5], 0, v[0:1]
	s_lshl_b32 s88, s27, 7
	v_lshl_add_u64 v[0:1], v[0:1], 0, s[88:89]
	v_lshlrev_b32_e32 v184, 6, v60
	v_lshl_add_u64 v[8:9], v[0:1], 0, v[184:185]
	global_load_dwordx4 v[0:3], v[8:9], off offset:512
	global_load_dwordx4 v[4:7], v[8:9], off offset:528
	global_load_dwordx4 v[10:13], v[8:9], off offset:544
	global_load_dwordx4 v[18:21], v[8:9], off offset:560
	global_load_dword v61, v185, s[36:37]
	global_load_dword v62, v185, s[36:37] offset:16
	global_load_dwordx4 v[156:159], v[8:9], off offset:1024
	global_load_dwordx4 v[160:163], v[8:9], off offset:1040
	global_load_dwordx4 v[164:167], v[8:9], off offset:1056
	global_load_dwordx4 v[168:171], v[8:9], off offset:1072
	v_readlane_b32 s16, v253, 28
	v_readlane_b32 s17, v253, 29
	s_andn2_b64 vcc, exec, s[0:1]
	v_readlane_b32 s42, v253, 50
	v_readlane_b32 s43, v253, 51
	v_readlane_b32 s44, v253, 52
	v_readlane_b32 s45, v253, 53
	v_readlane_b32 s46, v253, 54
	v_readlane_b32 s47, v253, 55
	v_readlane_b32 s48, v253, 56
	v_readlane_b32 s49, v253, 57
	s_nop 1
	v_readlane_b32 s53, v253, 61
	v_readlane_b32 s54, v253, 62
	v_readlane_b32 s55, v253, 63
	s_nop 1
	s_waitcnt vmcnt(9)
	v_lshlrev_b32_e32 v42, 16, v0
	v_and_b32_e32 v43, 0xffff0000, v0
	v_lshlrev_b32_e32 v40, 16, v1
	v_and_b32_e32 v41, 0xffff0000, v1
	v_lshlrev_b32_e32 v38, 16, v2
	v_and_b32_e32 v39, 0xffff0000, v2
	v_lshlrev_b32_e32 v36, 16, v3
	v_and_b32_e32 v37, 0xffff0000, v3
	s_waitcnt vmcnt(8)
	v_lshlrev_b32_e32 v34, 16, v4
	v_and_b32_e32 v35, 0xffff0000, v4
	v_lshlrev_b32_e32 v32, 16, v5
	v_and_b32_e32 v33, 0xffff0000, v5
	v_lshlrev_b32_e32 v30, 16, v6
	v_and_b32_e32 v31, 0xffff0000, v6
	v_lshlrev_b32_e32 v28, 16, v7
	s_waitcnt vmcnt(7)
	v_lshlrev_b32_e32 v26, 16, v10
	v_and_b32_e32 v27, 0xffff0000, v10
	v_lshlrev_b32_e32 v24, 16, v11
	v_and_b32_e32 v25, 0xffff0000, v11
	v_lshlrev_b32_e32 v22, 16, v12
	v_and_b32_e32 v23, 0xffff0000, v12
	v_lshlrev_b32_e32 v16, 16, v13
	v_and_b32_e32 v17, 0xffff0000, v13
	s_waitcnt vmcnt(6)
	v_lshlrev_b32_e32 v14, 16, v18
	v_and_b32_e32 v15, 0xffff0000, v18
	v_lshlrev_b32_e32 v12, 16, v19
	v_and_b32_e32 v13, 0xffff0000, v19
	v_lshlrev_b32_e32 v10, 16, v20
	v_and_b32_e32 v11, 0xffff0000, v20
	v_lshlrev_b32_e32 v20, 16, v21
	v_and_b32_e32 v19, 0xffff0000, v7
	v_and_b32_e32 v18, 0xffff0000, v21
	s_cbranch_vccnz .LBB0_256
	v_add_u32_e32 v0, s23, v59
	v_ashrrev_i32_e32 v1, 31, v0
	v_lshlrev_b64 v[0:1], 8, v[0:1]
	v_lshl_add_u64 v[0:1], s[16:17], 0, v[0:1]
	v_lshl_add_u64 v[44:45], v[0:1], 0, v[184:185]
	global_load_dwordx4 v[4:7], v[44:45], off offset:48
	global_load_dwordx4 v[54:57], v[44:45], off offset:32
	global_load_dwordx4 v[50:53], v[44:45], off offset:16
	global_load_dwordx4 v[46:49], v[44:45], off
	global_load_dwordx4 v[0:3], v[44:45], off offset:176
	global_load_dwordx4 v[64:67], v[44:45], off offset:160
	global_load_dwordx4 v[68:71], v[44:45], off offset:144
	global_load_dwordx4 v[72:75], v[44:45], off offset:128
	v_mov_b32_e32 v21, v18
	v_mov_b32_e32 v29, v19
	s_waitcnt vmcnt(0)
	v_pk_mul_f32 v[44:45], v[72:73], v[26:27]
	s_nop 0
	v_pk_fma_f32 v[44:45], v[46:47], v[42:43], v[44:45] neg_lo:[0,0,1] neg_hi:[0,0,1]
	v_pk_mul_f32 v[42:43], v[72:73], v[42:43]
	s_nop 0
	v_pk_fma_f32 v[26:27], v[46:47], v[26:27], v[42:43]
	v_pk_mul_f32 v[42:43], v[74:75], v[24:25]
	s_nop 0
	v_pk_fma_f32 v[46:47], v[48:49], v[40:41], v[42:43] neg_lo:[0,0,1] neg_hi:[0,0,1]
	v_pk_mul_f32 v[40:41], v[74:75], v[40:41]
	v_mov_b32_e32 v42, v44
	v_pk_fma_f32 v[24:25], v[48:49], v[24:25], v[40:41]
	v_pk_mul_f32 v[40:41], v[68:69], v[22:23]
	v_mov_b32_e32 v43, v45
	v_pk_fma_f32 v[48:49], v[50:51], v[38:39], v[40:41] neg_lo:[0,0,1] neg_hi:[0,0,1]
	v_pk_mul_f32 v[38:39], v[68:69], v[38:39]
	v_mov_b32_e32 v40, v46
	v_pk_fma_f32 v[22:23], v[50:51], v[22:23], v[38:39]
	v_pk_mul_f32 v[38:39], v[70:71], v[16:17]
	v_mov_b32_e32 v41, v47
	v_pk_fma_f32 v[50:51], v[52:53], v[36:37], v[38:39] neg_lo:[0,0,1] neg_hi:[0,0,1]
	v_pk_mul_f32 v[36:37], v[70:71], v[36:37]
	v_mov_b32_e32 v38, v48
	v_pk_fma_f32 v[16:17], v[52:53], v[16:17], v[36:37]
	v_pk_mul_f32 v[36:37], v[64:65], v[14:15]
	v_mov_b32_e32 v39, v49
	v_pk_fma_f32 v[52:53], v[54:55], v[34:35], v[36:37] neg_lo:[0,0,1] neg_hi:[0,0,1]
	v_pk_mul_f32 v[34:35], v[64:65], v[34:35]
	v_mov_b32_e32 v36, v50
	v_pk_fma_f32 v[14:15], v[54:55], v[14:15], v[34:35]
	v_pk_mul_f32 v[34:35], v[66:67], v[12:13]
	v_mov_b32_e32 v37, v51
	v_pk_fma_f32 v[54:55], v[56:57], v[32:33], v[34:35] neg_lo:[0,0,1] neg_hi:[0,0,1]
	v_pk_mul_f32 v[32:33], v[66:67], v[32:33]
	v_mov_b32_e32 v34, v52
	v_pk_fma_f32 v[12:13], v[56:57], v[12:13], v[32:33]
	v_pk_mul_f32 v[32:33], v[0:1], v[10:11]
	v_pk_mul_f32 v[0:1], v[0:1], v[30:31]
	v_pk_fma_f32 v[56:57], v[4:5], v[30:31], v[32:33] neg_lo:[0,0,1] neg_hi:[0,0,1]
	v_pk_fma_f32 v[10:11], v[4:5], v[10:11], v[0:1]
	v_pk_mul_f32 v[0:1], v[2:3], v[20:21]
	v_mul_f32_e32 v4, v2, v28
	v_mov_b32_e32 v2, v7
	v_pk_mul_f32 v[2:3], v[2:3], v[18:19]
	v_pk_fma_f32 v[0:1], v[6:7], v[28:29], v[0:1] neg_lo:[0,0,1] neg_hi:[0,0,1]
	v_mul_f32_e32 v6, v6, v20
	v_mov_b32_e32 v7, v2
	v_mov_b32_e32 v5, v3
	v_pk_add_f32 v[20:21], v[6:7], v[4:5]
	v_mov_b32_e32 v35, v53
	v_mov_b32_e32 v32, v54
	v_mov_b32_e32 v33, v55
	v_mov_b32_e32 v30, v56
	v_mov_b32_e32 v31, v57
	v_mov_b32_e32 v28, v0
	v_mov_b32_e32 v19, v1
	v_mov_b32_e32 v18, v21
	s_branch .LBB0_256
